# GEMM phase prologues: second K-tile's LDS-DMA loads issued before the wait for the first K-tile
# baseline (speedup 1.0000x reference)
; #define PG8_STAGE(bufoff, gbase, voff) do { _Pragma("unroll") for (int _i = 0; _i < 2; ++_i) \
;         __builtin_amdgcn_global_load_lds((const unsigned*)((const char*)(gbase) + (voff)[_i]), (PG8_LAS unsigned*)(lds + (bufoff) + ldsw + _i * 8192), 16, 0, 0); } while (0)
; #define PG8_WAIT_V(n) asm volatile("s_waitcnt vmcnt(" #n ")" ::: "memory")
; #define PG8_BAR __builtin_amdgcn_s_barrier()
; template <class Epi, class Sched, bool ALIGN_EPI = false, bool SP2 = false>
; __device__ __forceinline__ void gemm_phase(PG8_LAS unsigned char* lds, const Gemm g, const Sched& S, const Epi& E) {
;     ...
;         PG8_STAGE(PG8_SB(0, 0), cB, voffB); PG8_STAGE(PG8_SB(0, 1), cB + hstep, voffB); PG8_STAGE(PG8_SA(0, 0), cA, voffA); PG8_STAGE(PG8_SA(0, 1), cA + hstep, voffA);
;         if (wr == 1) PG8_BAR;
;         PG8_WAIT_V(2); PG8_BAR;
;         PG8_STAGE(PG8_SB(1, 0), cB + kstep, voffB); PG8_STAGE(PG8_SA(1, 0), cA + kstep, voffA); PG8_STAGE(PG8_SB(1, 1), cB + hstep + kstep, voffB);
;         PG8_WAIT_V(6); PG8_BAR;
.LBB0_228:
	s_mov_b64 s[20:21], 0x80
	s_and_b32 s7, s4, 3
	s_add_i32 m0, s41, 0x18000
	v_lshl_add_u64 v[8:9], v[8:9], 0, s[20:21]
	s_lshl_b32 s26, s5, 6
	s_lshl_b32 s23, s5, 13
	s_lshl_b32 s27, s7, 12
	global_load_lds_dwordx4 v[8:9], off
	v_lshl_add_u64 v[6:7], v[6:7], 0, s[20:21]
	s_add_i32 m0, s41, 0x1a000
	s_add_i32 s57, s41, 0x8000
	s_add_i32 s58, s41, 0xa000
	global_load_lds_dwordx4 v[6:7], off
	v_lshl_add_u64 v[4:5], v[4:5], 0, s[20:21]
	s_mov_b32 m0, s57
	s_add_u32 s4, s44, 0x40080
	global_load_lds_dwordx4 v[4:5], off
	v_lshl_add_u64 v[2:3], v[2:3], 0, s[20:21]
	s_mov_b32 m0, s58
	s_addc_u32 s5, s45, 0
	global_load_lds_dwordx4 v[2:3], off
	s_add_i32 m0, s41, 0x1c000
	v_lshl_add_u64 v[2:3], s[4:5], 0, v[132:133]
	global_load_lds_dwordx4 v[2:3], off
	v_lshl_add_u64 v[2:3], s[4:5], 0, v[136:137]
	s_add_i32 m0, s41, 0x1e000
	v_bfe_u32 v4, v10, 4, 2
	global_load_lds_dwordx4 v[2:3], off
	s_waitcnt vmcnt(8)
	s_barrier
	v_and_b32_e32 v3, 15, v10
	v_lshlrev_b32_e32 v2, 3, v4
	v_lshlrev_b32_e32 v4, 4, v4
	v_lshlrev_b32_e32 v5, 2, v10
	v_lshl_or_b32 v4, v3, 6, v4
	v_and_b32_e32 v5, 32, v5
	s_cmpk_lt_u32 s22, 0x100
	v_bitop3_b32 v6, v4, s23, v5 bitop3:0xde
	s_cselect_b64 s[22:23], -1, 0
	s_ashr_i32 s4, s26, 31
	v_or_b32_e32 v140, s26, v3
	v_mov_b32_e32 v141, s4
	s_lshl_b32 s4, s7, 4
	v_lshrrev_b32_e32 v3, 2, v10
	v_and_or_b32 v3, v3, 8, s4
	v_bitop3_b32 v172, v4, s27, v5 bitop3:0xde
	v_and_b32_e32 v4, 16, v10
	v_or_b32_e32 v174, 0xfffffe00, v3
	v_lshlrev_b32_e32 v3, 14, v11
	v_cmp_eq_u32_e32 vcc, 0, v4
	v_lshl_or_b32 v4, s7, 5, v2
	v_and_b32_e32 v3, 0xffff8000, v3
	v_or_b32_e32 v173, 0xfffff800, v4
	v_lshl_add_u32 v3, v12, 11, v3
	v_and_b32_e32 v4, 1, v11
	v_lshl_or_b32 v3, v4, 6, v3
	v_lshl_add_u32 v144, v13, 1, v3
	v_lshlrev_b32_e32 v3, 14, v14
	s_ashr_i32 s61, s29, 31
	s_ashr_i32 s62, s14, 31
	v_and_b32_e32 v3, 0xffff8000, v3
	s_waitcnt vmcnt(6)
	v_bfrev_b32_e32 v5, 8
	v_mov_b32_e32 v7, 0xe000000
	s_add_u32 s26, s12, 0x14000000
	v_lshl_add_u32 v3, v15, 11, v3
	v_and_b32_e32 v4, 1, v14
	v_cndmask_b32_e32 v138, v5, v7, vcc
	s_addc_u32 s27, s13, 0
	v_lshl_or_b32 v3, v4, 6, v3
	s_add_i32 s64, 0, 0x10000
	s_add_i32 s65, 0, 0x14000
	s_mov_b32 s59, 0x18000
	s_mov_b32 s60, 0x8000
	v_lshl_add_u64 v[142:143], s[12:13], 0, v[138:139]
	v_lshl_or_b32 v175, s7, 6, v2
	v_mov_b32_e32 v145, v139
	v_lshl_add_u32 v146, v16, 1, v3
	v_mov_b32_e32 v147, v139
	v_mov_b64_e32 v[148:149], 0xc00
	v_mov_b64_e32 v[150:151], 0xbff
	s_movk_i32 s63, 0x181
	v_add_u32_e32 v176, s64, v172
	v_add_u32_e32 v177, s65, v172
	v_add_u32_e32 v178, 0, v6
	s_mov_b32 s66, 0xc000
	s_brev_b32 s67, 48
	s_movk_i32 s68, 0xfa00
	s_mov_b32 s69, 0x20000
	s_mov_b32 s70, 0x24000
	s_mov_b32 s71, 0x28000
	s_mov_b32 s72, 0x2c000
	s_mov_b32 s28, 0x437f0000
	s_mov_b32 s73, 0x40000
	s_mov_b32 s74, 0x48000
	s_mov_b32 s75, 0x50000
	v_lshlrev_b32_e32 v179, 2, v2
	s_mov_b32 s76, 0x6000000
	v_mov_b32_e32 v180, 0x358637bd
	v_mov_b32_e32 v181, 0x3e38aa3b
	s_barrier
	s_branch .LBB0_231

; #define PG8_STAGE(bufoff, gbase, voff) do { _Pragma("unroll") for (int _i = 0; _i < 2; ++_i) \
;         __builtin_amdgcn_global_load_lds((const unsigned*)((const char*)(gbase) + (voff)[_i]), (PG8_LAS unsigned*)(lds + (bufoff) + ldsw + _i * 8192), 16, 0, 0); } while (0)
; #define PG8_WAIT_V(n) asm volatile("s_waitcnt vmcnt(" #n ")" ::: "memory")
; #define PG8_BAR __builtin_amdgcn_s_barrier()
; template <class Epi, class Sched, bool ALIGN_EPI = false, bool SP2 = false>
; __device__ __forceinline__ void gemm_phase(PG8_LAS unsigned char* lds, const Gemm g, const Sched& S, const Epi& E) {
;     ...
;         PG8_STAGE(PG8_SB(0, 0), cB, voffB); PG8_STAGE(PG8_SB(0, 1), cB + hstep, voffB); PG8_STAGE(PG8_SA(0, 0), cA, voffA); PG8_STAGE(PG8_SA(0, 1), cA + hstep, voffA);
;         if (wr == 1) PG8_BAR;
;         PG8_WAIT_V(2); PG8_BAR;
;         PG8_STAGE(PG8_SB(1, 0), cB + kstep, voffB); PG8_STAGE(PG8_SA(1, 0), cA + kstep, voffA); PG8_STAGE(PG8_SB(1, 1), cB + hstep + kstep, voffB);
;         PG8_WAIT_V(6); PG8_BAR;
.LBB0_497:
	s_add_u32 s8, s4, 0x8000000
	s_addc_u32 s9, s5, 0
	s_add_u32 s10, s4, 0x14000000
	s_addc_u32 s11, s5, 0
	s_lshl_b32 s4, s12, 5
	s_mov_b64 s[12:13], 0x80
	s_and_b32 s21, s4, 0x60
	s_add_i32 m0, s46, 0x18000
	v_lshl_add_u64 v[10:11], v[10:11], 0, s[12:13]
	s_lshl_b32 s20, s16, 13
	s_lshl_b32 s22, s21, 7
	global_load_lds_dwordx4 v[10:11], off
	v_lshl_add_u64 v[8:9], v[8:9], 0, s[12:13]
	s_add_i32 m0, s46, 0x1a000
	s_add_i32 s51, s46, 0x8000
	s_add_i32 s52, s46, 0xa000
	global_load_lds_dwordx4 v[8:9], off
	v_lshl_add_u64 v[4:5], v[4:5], 0, s[12:13]
	s_mov_b32 m0, s51
	s_add_u32 s4, s36, 0x40080
	global_load_lds_dwordx4 v[4:5], off
	v_lshl_add_u64 v[4:5], v[6:7], 0, s[12:13]
	s_mov_b32 m0, s52
	s_addc_u32 s5, s37, 0
	global_load_lds_dwordx4 v[4:5], off
	s_add_i32 m0, s46, 0x1c000
	v_lshl_add_u64 v[4:5], s[4:5], 0, v[154:155]
	global_load_lds_dwordx4 v[4:5], off
	v_lshl_add_u64 v[4:5], s[4:5], 0, v[158:159]
	s_add_i32 m0, s46, 0x1e000
	s_mov_b64 s[4:5], 0x40080
	global_load_lds_dwordx4 v[4:5], off
	s_waitcnt vmcnt(8)
	s_barrier
	v_lshrrev_b32_e32 v5, 1, v1
	v_and_b32_e32 v5, 24, v5
	v_and_b32_e32 v4, 15, v1
	v_lshlrev_b32_e32 v6, 1, v5
	v_lshl_or_b32 v6, v4, 6, v6
	v_lshlrev_b32_e32 v4, 10, v4
	v_lshl_or_b32 v4, s16, 16, v4
	v_or3_b32 v174, v5, v4, s21
	v_lshlrev_b32_e32 v4, 14, v2
	v_and_b32_e32 v4, 0xffff8000, v4
	v_lshl_add_u32 v4, v12, 11, v4
	v_and_b32_e32 v2, 1, v2
	v_lshl_or_b32 v2, v2, 6, v4
	v_lshl_add_u32 v2, v13, 1, v2
	v_lshl_add_u64 v[160:161], v[2:3], 0, s[4:5]
	v_lshlrev_b32_e32 v2, 14, v14
	v_and_b32_e32 v2, 0xffff8000, v2
	v_lshlrev_b32_e32 v1, 2, v1
	v_lshl_add_u32 v2, v15, 11, v2
	v_and_b32_e32 v4, 1, v14
	v_and_b32_e32 v1, 32, v1
	s_waitcnt vmcnt(6)
	v_lshl_or_b32 v2, v4, 6, v2
	v_bitop3_b32 v7, v6, s20, v1 bitop3:0xde
	s_cmpk_lt_u32 s15, 0x100
	v_lshl_add_u32 v2, v16, 1, v2
	s_sext_i32_i8 s35, s14
	v_bitop3_b32 v1, v6, s22, v1 bitop3:0xde
	s_cselect_b64 s[14:15], -1, 0
	s_ashr_i32 s53, s33, 31
	v_lshl_add_u64 v[162:163], v[2:3], 0, s[4:5]
	v_mov_b64_e32 v[164:165], 0x200
	v_mov_b64_e32 v[166:167], 0x1ff
	s_add_i32 s54, 0, 0x10000
	s_add_i32 s55, 0, 0x14000
	v_add_u32_e32 v175, 0, v7
	s_mov_b32 s16, 0x3b808081
	s_barrier
	s_branch .LBB0_500

; #define PG8_STAGE(bufoff, gbase, voff) do { _Pragma("unroll") for (int _i = 0; _i < 2; ++_i) \
;         __builtin_amdgcn_global_load_lds((const unsigned*)((const char*)(gbase) + (voff)[_i]), (PG8_LAS unsigned*)(lds + (bufoff) + ldsw + _i * 8192), 16, 0, 0); } while (0)
; #define PG8_WAIT_V(n) asm volatile("s_waitcnt vmcnt(" #n ")" ::: "memory")
; #define PG8_BAR __builtin_amdgcn_s_barrier()
; template <class Epi, class Sched, bool ALIGN_EPI = false, bool SP2 = false>
; __device__ __forceinline__ void gemm_phase(PG8_LAS unsigned char* lds, const Gemm g, const Sched& S, const Epi& E) {
;     ...
;         PG8_STAGE(PG8_SB(0, 0), cB, voffB); PG8_STAGE(PG8_SB(0, 1), cB + hstep, voffB); PG8_STAGE(PG8_SA(0, 0), cA, voffA); PG8_STAGE(PG8_SA(0, 1), cA + hstep, voffA);
;         if (wr == 1) PG8_BAR;
;         PG8_WAIT_V(2); PG8_BAR;
;         PG8_STAGE(PG8_SB(1, 0), cB + kstep, voffB); PG8_STAGE(PG8_SA(1, 0), cA + kstep, voffA); PG8_STAGE(PG8_SB(1, 1), cB + hstep + kstep, voffB);
;         PG8_WAIT_V(6); PG8_BAR;
.LBB0_575:
	s_add_u32 s50, s10, 0x2000
	s_addc_u32 s51, s11, 0
	s_lshl_b32 s0, s15, 5
	s_mov_b64 s[10:11], 0x80
	s_and_b32 s15, s0, 0x60
	s_add_i32 m0, s45, 0x18000
	v_lshl_add_u64 v[8:9], v[8:9], 0, s[10:11]
	s_lshl_b32 s16, s14, 6
	s_lshl_b32 s14, s14, 13
	s_lshl_b32 s17, s15, 7
	global_load_lds_dwordx4 v[8:9], off
	v_lshl_add_u64 v[6:7], v[6:7], 0, s[10:11]
	s_add_i32 m0, s45, 0x1a000
	s_add_i32 s52, s45, 0x8000
	s_add_i32 s53, s45, 0xa000
	global_load_lds_dwordx4 v[6:7], off
	v_lshl_add_u64 v[2:3], v[2:3], 0, s[10:11]
	s_mov_b32 m0, s52
	s_add_u32 s0, s36, 0x40080
	global_load_lds_dwordx4 v[2:3], off
	v_lshl_add_u64 v[2:3], v[4:5], 0, s[10:11]
	s_mov_b32 m0, s53
	s_addc_u32 s1, s37, 0
	global_load_lds_dwordx4 v[2:3], off
	s_add_i32 m0, s45, 0x1c000
	v_lshl_add_u64 v[2:3], s[0:1], 0, v[144:145]
	global_load_lds_dwordx4 v[2:3], off
	v_lshl_add_u64 v[2:3], s[0:1], 0, v[146:147]
	s_add_i32 m0, s45, 0x1e000
	v_bfe_u32 v4, v0, 4, 2
	global_load_lds_dwordx4 v[2:3], off
	s_waitcnt vmcnt(8)
	s_barrier
	v_and_b32_e32 v2, 15, v0
	v_lshlrev_b32_e32 v3, 4, v4
	v_lshlrev_b32_e32 v0, 2, v0
	v_lshl_or_b32 v3, v2, 6, v3
	v_and_b32_e32 v0, 32, v0
	v_bitop3_b32 v5, v3, s14, v0 bitop3:0xde
	v_bitop3_b32 v162, v3, s17, v0 bitop3:0xde
	v_lshlrev_b32_e32 v0, 14, v1
	v_and_b32_e32 v0, 0xffff8000, v0
	v_lshl_add_u32 v0, v10, 11, v0
	v_and_b32_e32 v1, 1, v1
	v_lshl_or_b32 v0, v1, 6, v0
	v_lshl_add_u32 v150, v11, 1, v0
	v_lshlrev_b32_e32 v0, 14, v12
	s_cmpk_lt_u32 s13, 0x100
	v_and_b32_e32 v0, 0xffff8000, v0
	s_sext_i32_i8 s61, s12
	s_waitcnt vmcnt(6)
	s_cselect_b64 s[12:13], -1, 0
	s_ashr_i32 s0, s16, 31
	v_lshl_add_u32 v0, v13, 11, v0
	v_and_b32_e32 v1, 1, v12
	v_or_b32_e32 v2, s16, v2
	v_mov_b32_e32 v3, s0
	v_lshl_or_b32 v0, v1, 6, v0
	s_add_i32 s55, 0, 0x10000
	s_add_i32 s56, 0, 0x14000
	v_lshlrev_b64 v[148:149], 12, v[2:3]
	s_ashr_i32 s54, s3, 31
	v_lshl_or_b32 v163, v4, 2, s15
	v_mov_b32_e32 v151, v145
	v_lshl_add_u32 v152, v14, 1, v0
	v_mov_b32_e32 v153, v145
	v_mov_b64_e32 v[154:155], 0x200
	v_mov_b64_e32 v[156:157], 0x1ff
	v_add_u32_e32 v164, s55, v162
	v_add_u32_e32 v165, s56, v162
	v_add_u32_e32 v166, 0, v5
	s_mov_b64 s[14:15], 0x80000
	s_mov_b32 s57, 0x80000
	s_mov_b64 s[16:17], 0x90000
	s_mov_b32 s58, 0x90000
	s_mov_b64 s[18:19], 0xa0000
	s_mov_b32 s59, 0xa0000
	s_mov_b64 s[20:21], 0xb0000
	s_mov_b32 s60, 0xb0000
	s_barrier
	s_branch .LBB0_578
